# P5 up-proj epilogue: per-CU LDS table of row sums replaces 8 serialized SSQ loads + 16 bpermute round trips
# speedup vs baseline: 1.0222x; 1.0222x over previous
.LBB0_568:
	s_andn2_b64 vcc, exec, s[4:5]
	s_cbranch_vccnz .LBB0_597
	s_waitcnt lgkmcnt(0)
	s_lshl_b32 s7, s60, 8
	v_add_u32_e32 v0, s7, v9
	v_lshlrev_b32_e32 v0, 6, v0
	s_add_u32 s10, s70, 0x1b00000
	s_addc_u32 s11, s71, 0
	v_cmp_gt_u32_e32 vcc, 0x100, v9
	s_and_saveexec_b64 s[14:15], vcc
	s_cbranch_execz .Lssq_tab_done
	global_load_dwordx4 v[12:15], v0, s[10:11]
	global_load_dwordx4 v[16:19], v0, s[10:11] offset:16
	global_load_dwordx4 v[20:23], v0, s[10:11] offset:32
	global_load_dwordx4 v[24:27], v0, s[10:11] offset:48
	v_lshlrev_b32_e32 v1, 2, v9
	v_add_u32_e32 v1, 0x22000, v1
	s_waitcnt vmcnt(0)
	v_add_f32_e32 v12, v13, v12
	v_add_f32_e32 v14, v14, v15
	v_add_f32_e32 v16, v17, v16
	v_add_f32_e32 v18, v18, v19
	v_add_f32_e32 v20, v21, v20
	v_add_f32_e32 v22, v22, v23
	v_add_f32_e32 v24, v25, v24
	v_add_f32_e32 v26, v26, v27
	v_add_f32_e32 v12, v12, v14
	v_add_f32_e32 v16, v16, v18
	v_add_f32_e32 v20, v20, v22
	v_add_f32_e32 v24, v24, v26
	v_add_f32_e32 v12, v12, v16
	v_add_f32_e32 v20, v20, v24
	v_add_f32_e32 v12, v12, v20
	ds_write_b32 v1, v12
.Lssq_tab_done:
	s_or_b64 exec, exec, s[14:15]
	v_ashrrev_i32_e32 v1, 31, v9
	v_lshrrev_b32_e32 v1, 26, v1
	v_add_u32_e32 v1, v9, v1
	v_ashrrev_i32_e32 v8, 6, v1
	v_bfe_i32 v1, v9, 27, 1
	v_lshlrev_b32_e32 v0, 4, v9
	v_lshrrev_b32_e32 v1, 22, v1
	v_add_u32_e32 v1, v0, v1
	v_and_b32_e32 v1, 0xfffffc00, v1
	v_sub_u32_e32 v1, v0, v1
	v_lshrrev_b32_e32 v2, 4, v1
	v_bitop3_b32 v1, v2, v1, 32 bitop3:0x6c
	v_ashrrev_i32_e32 v3, 31, v1
	v_lshrrev_b32_e32 v3, 26, v3
	v_add_u32_e32 v3, v1, v3
	v_lshlrev_b32_e32 v2, 3, v8
	v_ashrrev_i32_e32 v10, 6, v3
	v_and_b32_e32 v3, 0xc0, v3
	v_and_b32_e32 v2, -16, v2
	v_sub_u32_e32 v1, v1, v3
	v_mov_b32_e32 v3, 1
	v_add_u32_e32 v2, v10, v2
	v_ashrrev_i16_sdwa v1, v3, sext(v1) dst_sel:DWORD dst_unused:UNUSED_PAD src0_sel:DWORD src1_sel:BYTE_0
	v_lshlrev_b32_e32 v4, 5, v8
	v_bfe_i32 v11, v1, 0, 16
	v_lshlrev_b32_e32 v1, 1, v2
	v_lshrrev_b32_e32 v5, 2, v2
	v_and_b32_e32 v6, 3, v10
	s_mov_b32 s4, 0x1fffe0
	v_and_b32_e32 v4, 32, v4
	v_and_b32_e32 v1, 24, v1
	v_and_b32_e32 v5, 4, v5
	v_and_or_b32 v6, v2, s4, v6
	v_or3_b32 v1, v6, v5, v1
	v_add_lshl_u32 v4, v4, v11, 1
	v_add_u32_e32 v0, 0x2000, v0
	v_lshl_add_u32 v194, v1, 11, v4
	v_ashrrev_i32_e32 v1, 31, v0
	v_lshrrev_b32_e32 v1, 22, v1
	v_add_u32_e32 v1, v0, v1
	v_ashrrev_i32_e32 v12, 10, v1
	v_mul_i32_i24_e32 v1, 0x400, v12
	v_sub_u32_e32 v0, v0, v1
	v_lshrrev_b32_e32 v1, 4, v0
	v_bitop3_b32 v0, v1, v0, 32 bitop3:0x6c
	v_lshl_add_u32 v192, v2, 11, v4
	v_ashrrev_i32_e32 v2, 31, v0
	v_lshrrev_b32_e32 v2, 26, v2
	v_add_u32_e32 v2, v0, v2
	s_add_u32 s3, s70, 0x2000000
	v_lshlrev_b32_e32 v1, 3, v12
	v_ashrrev_i32_e32 v13, 6, v2
	v_and_b32_e32 v2, 0xc0, v2
	s_addc_u32 s66, s71, 0
	v_and_b32_e32 v1, -16, v1
	v_sub_u32_e32 v0, v0, v2
	s_add_u32 s67, s70, 0x800000
	v_add_u32_e32 v1, v13, v1
	v_ashrrev_i16_sdwa v0, v3, sext(v0) dst_sel:DWORD dst_unused:UNUSED_PAD src0_sel:DWORD src1_sel:BYTE_0
	v_and_b32_e32 v3, 3, v13
	s_addc_u32 s72, s71, 0
	v_and_or_b32 v3, v1, s4, v3
	s_ashr_i32 s4, s6, 6
	s_ashr_i32 s61, s60, 31
	s_ashr_i32 s59, s58, 31
	s_ashr_i32 s7, s6, 8
	s_lshl_b32 s73, s4, 10
	s_lshl_b64 s[8:9], s[60:61], 19
	s_lshl_b64 s[10:11], s[58:59], 19
	s_add_u32 s62, s67, s10
	v_lshlrev_b32_e32 v4, 5, v12
	v_bfe_i32 v14, v0, 0, 16
	v_lshlrev_b32_e32 v0, 1, v1
	v_lshrrev_b32_e32 v2, 2, v1
	s_addc_u32 s63, s72, s11
	s_add_i32 s74, s73, 0
	v_and_b32_e32 v4, 32, v4
	v_and_b32_e32 v0, 24, v0
	v_and_b32_e32 v2, 4, v2
	s_add_i32 m0, s74, 0x10000
	v_or3_b32 v0, v3, v2, v0
	v_add_lshl_u32 v2, v4, v14, 1
	global_load_lds_dwordx4 v194, s[62:63]
	s_add_i32 m0, s74, 0x12000
	v_lshl_add_u32 v200, v0, 11, v2
	s_add_u32 s10, s62, 0x40000
	global_load_lds_dwordx4 v200, s[62:63]
	s_addc_u32 s11, s63, 0
	s_add_i32 m0, s74, 0x14000
	v_lshl_add_u32 v198, v1, 11, v2
	global_load_lds_dwordx4 v194, s[10:11]
	s_add_i32 m0, s74, 0x16000
	s_add_u32 s8, s3, s8
	s_addc_u32 s9, s66, s9
	s_add_i32 s75, s74, 0x2000
	global_load_lds_dwordx4 v200, s[10:11]
	s_mov_b32 m0, s74
	s_add_u32 s10, s8, 0x40000
	global_load_lds_dwordx4 v192, s[8:9]
	s_mov_b32 m0, s75
	s_addc_u32 s11, s9, 0
	s_add_i32 s76, s74, 0x4000
	global_load_lds_dwordx4 v198, s[8:9]
	s_mov_b32 m0, s76
	s_add_i32 s77, s74, 0x6000
	global_load_lds_dwordx4 v192, s[10:11]
	s_mov_b32 m0, s77
	v_writelane_b32 v255, s95, 1
	global_load_lds_dwordx4 v198, s[10:11]
	v_writelane_b32 v255, s94, 2
	v_mov_b32_e32 v203, 0
	v_writelane_b32 v255, s92, 3
	v_mov_b32_e32 v195, v203
	v_mov_b32_e32 v201, v203
	v_mov_b32_e32 v193, v203
	v_mov_b32_e32 v199, v203
	s_cmp_eq_u32 s7, 1
	v_writelane_b32 v255, s93, 4
	s_mov_b32 s10, 2
	s_movk_i32 s78, 0x2000
	s_mov_b32 s79, 0
	v_lshl_add_u64 v[6:7], s[62:63], 0, v[194:195]
	v_lshl_add_u64 v[4:5], s[62:63], 0, v[200:201]
	v_lshl_add_u64 v[2:3], s[8:9], 0, v[192:193]
	v_lshl_add_u64 v[0:1], s[8:9], 0, v[198:199]
	s_cselect_b64 s[14:15], -1, 0
	s_cmp_lg_u32 s7, 1
	s_mov_b32 s11, 2
	s_cbranch_scc1 .LBB0_571
	s_mov_b32 s11, 0
	s_mov_b32 s10, 4
	s_barrier

.LBB0_580:
	v_lshl_add_u32 v222, s60, 8, v197
	v_lshl_or_b32 v220, s58, 7, v206
	v_ashrrev_i32_e32 v221, 31, v220
	v_lshlrev_b64 v[116:117], 2, v[220:221]
	v_lshl_add_u64 v[118:119], s[38:39], 0, v[116:117]
	v_lshl_add_u64 v[242:243], s[24:25], 0, v[116:117]
	global_load_dwordx4 v[124:127], v[118:119], off
	v_lshl_add_u64 v[238:239], s[22:23], 0, v[116:117]
	v_lshl_add_u64 v[118:119], s[40:41], 0, v[116:117]
	global_load_dwordx4 v[120:123], v[242:243], off
	global_load_dwordx4 v[140:143], v[238:239], off
	v_lshl_add_u64 v[132:133], s[42:43], 0, v[116:117]
	global_load_dwordx4 v[128:131], v[118:119], off
	global_load_dwordx4 v[144:147], v[132:133], off
	v_lshl_add_u64 v[118:119], s[44:45], 0, v[116:117]
	v_lshl_add_u64 v[136:137], s[46:47], 0, v[116:117]
	v_lshl_add_u64 v[116:117], s[48:49], 0, v[116:117]
	global_load_dwordx4 v[132:135], v[118:119], off
	global_load_dwordx4 v[148:151], v[136:137], off
	s_nop 0
	global_load_dwordx4 v[136:139], v[116:117], off
	v_lshlrev_b32_e32 v254, 2, v197
	v_add_u32_e32 v254, 0x22000, v254
	ds_read_b32 v176, v254
	ds_read_b32 v240, v254 offset:64
	ds_read_b32 v223, v254 offset:128
	ds_read_b32 v178, v254 offset:192
	ds_read_b32 v229, v254 offset:512
	ds_read_b32 v233, v254 offset:576
	ds_read_b32 v235, v254 offset:640
	ds_read_b32 v179, v254 offset:704
	v_or_b32_e32 v224, 16, v222
	v_or_b32_e32 v226, 32, v222
	v_or_b32_e32 v228, 48, v222
	v_add_u32_e32 v230, 0x80, v222
	v_add_u32_e32 v232, 0x90, v222
	v_add_u32_e32 v234, 0xa0, v222
	v_add_u32_e32 v236, 0xb0, v222
	v_mov_b32_e32 v177, 0
	v_mov_b32_e32 v253, 0
	v_mov_b32_e32 v225, 0
	v_mov_b32_e32 v231, 0
	v_mov_b32_e32 v241, 0
	v_mov_b32_e32 v252, 0
	s_waitcnt lgkmcnt(0)
	v_fmamk_f32 v178, v178, 0x3a800000, v249
	v_fmamk_f32 v179, v179, 0x3a800000, v249
	v_rsq_f32_e32 v180, v178
	v_rsq_f32_e32 v182, v179
	s_nop 1
	v_pk_mul_f32 v[186:187], v[86:87], v[180:181] op_sel_hi:[1,0]
	v_pk_mul_f32 v[184:185], v[84:85], v[180:181] op_sel_hi:[1,0]
	v_pk_mul_f32 v[110:111], v[82:83], v[180:181] op_sel_hi:[1,0]
	v_pk_mul_f32 v[108:109], v[80:81], v[180:181] op_sel_hi:[1,0]
	v_pk_mul_f32 v[190:191], v[78:79], v[180:181] op_sel_hi:[1,0]
	v_pk_mul_f32 v[188:189], v[76:77], v[180:181] op_sel_hi:[1,0]
	v_pk_mul_f32 v[118:119], v[74:75], v[180:181] op_sel_hi:[1,0]
	v_pk_mul_f32 v[116:117], v[72:73], v[180:181] op_sel_hi:[1,0]
	v_pk_mul_f32 v[170:171], v[50:51], v[182:183] op_sel_hi:[1,0]
	v_pk_mul_f32 v[168:169], v[48:49], v[182:183] op_sel_hi:[1,0]
	v_pk_mul_f32 v[74:75], v[42:43], v[182:183] op_sel_hi:[1,0]
	v_pk_mul_f32 v[72:73], v[40:41], v[182:183] op_sel_hi:[1,0]
	v_pk_mul_f32 v[174:175], v[34:35], v[182:183] op_sel_hi:[1,0]
	v_pk_mul_f32 v[172:173], v[32:33], v[182:183] op_sel_hi:[1,0]
	v_pk_mul_f32 v[78:79], v[26:27], v[182:183] op_sel_hi:[1,0]
	v_pk_mul_f32 v[76:77], v[24:25], v[182:183] op_sel_hi:[1,0]
	s_waitcnt vmcnt(0)
	v_cndmask_b32_e64 v24, 0, 1, s[14:15]
	v_cmp_ne_u32_e64 s[8:9], 1, v24
	s_and_saveexec_b64 s[62:63], s[4:5]
	s_cbranch_execz .LBB0_583
	s_and_b64 vcc, exec, s[8:9]
	ds_write_b128 v250, v[184:187]
	ds_write_b128 v250, v[108:111] offset:16
	ds_write_b128 v250, v[188:191] offset:512
	ds_write_b128 v250, v[116:119] offset:528
	ds_write_b128 v250, v[168:171] offset:4096
	ds_write_b128 v250, v[72:75] offset:4112
	ds_write_b128 v250, v[172:175] offset:4608
	ds_write_b128 v250, v[76:79] offset:4624
	s_cbranch_vccnz .LBB0_583
	s_ashr_i32 s61, s60, 31
	v_lshl_add_u64 v[24:25], s[60:61], 2, v[208:209]
	v_mov_b64_e32 v[26:27], s[18:19]
	s_lshl_b32 s10, s58, 8
	v_mad_u64_u32 v[26:27], s[64:65], v24, s91, v[26:27]
	s_ashr_i32 s11, s10, 31
	v_mad_i32_i24 v27, v25, s91, v27
	v_lshl_add_u64 v[24:25], s[10:11], 2, v[26:27]
	v_lshlrev_b32_e32 v202, 2, v206
	v_lshl_add_u64 v[24:25], v[24:25], 0, v[202:203]
	global_store_dwordx4 v[24:25], v[168:171], off
	global_store_dwordx4 v[24:25], v[72:75], off offset:16
	global_store_dwordx4 v[24:25], v[172:175], off offset:512
	global_store_dwordx4 v[24:25], v[76:79], off offset:528
